# adds: row scales read from LDS once per tile in the P1/P5 epilogues; integer RNE bf16 packs replaced by v_cvt_pk_bf16_f32 in the P3 epilogue and attention
# speedup vs baseline: 1.0036x; 1.0003x over previous
;     __device__ __forceinline__ void operator()(const f32x4 (&acc)[2][2][4][2], const Unit& u, int wr, int wc, int fr, int fq) const {
;     ...
;             for (int ai = 0; ai < 2; ++ai)
; #pragma unroll
;                 for (int m = 0; m < 4; ++m) {
;                     const int row = row0 + ai * HALF + m * 16; const float rs = rsc ? rsc[row - rbase] : rstd[row];
.LBB0_117:
	v_subrev_u32_e32 v147, s71, v148
	s_andn2_b64 vcc, exec, s[0:1]
	v_lshl_add_u32 v165, v147, 2, s86
	s_cbranch_vccnz .LBB0_119
	s_waitcnt vmcnt(0)
	ds_read_b32 v228, v165
	ds_read_b32 v229, v165 offset:64
	ds_read_b32 v230, v165 offset:128
	ds_read_b32 v231, v165 offset:192
	ds_read_b32 v232, v165 offset:512
	ds_read_b32 v233, v165 offset:576
	ds_read_b32 v234, v165 offset:640
	ds_read_b32 v235, v165 offset:704
	s_waitcnt lgkmcnt(0)
	v_mov_b32_e32 v150, v228

;     __device__ __forceinline__ void operator()(const f32x4 (&acc)[2][2][4][2], const Unit& u, int wr, int wc, int fr, int fq) const {
;     ...
;                 for (int m = 0; m < 4; ++m) {
;                     const int row = row0 + ai * HALF + m * 16; const float rs = rsc ? rsc[row - rbase] : rstd[row];
.LBB0_130:
	s_andn2_b64 vcc, exec, s[0:1]
	s_cbranch_vccnz .LBB0_132
	s_waitcnt vmcnt(0)
	v_mov_b32_e32 v126, v229

;     __device__ __forceinline__ void operator()(const f32x4 (&acc)[2][2][4][2], const Unit& u, int wr, int wc, int fr, int fq) const {
;     ...
;                 for (int m = 0; m < 4; ++m) {
;                     const int row = row0 + ai * HALF + m * 16; const float rs = rsc ? rsc[row - rbase] : rstd[row];
.LBB0_143:
	s_andn2_b64 vcc, exec, s[0:1]
	s_cbranch_vccnz .LBB0_145
	s_waitcnt vmcnt(0)
	v_mov_b32_e32 v118, v230

;     __device__ __forceinline__ void operator()(const f32x4 (&acc)[2][2][4][2], const Unit& u, int wr, int wc, int fr, int fq) const {
;     ...
;                 for (int m = 0; m < 4; ++m) {
;                     const int row = row0 + ai * HALF + m * 16; const float rs = rsc ? rsc[row - rbase] : rstd[row];
.LBB0_156:
	s_andn2_b64 vcc, exec, s[0:1]
	s_cbranch_vccnz .LBB0_158
	s_waitcnt vmcnt(0)
	v_mov_b32_e32 v110, v231

;     __device__ __forceinline__ void operator()(const f32x4 (&acc)[2][2][4][2], const Unit& u, int wr, int wc, int fr, int fq) const {
;     ...
;                 for (int m = 0; m < 4; ++m) {
;                     const int row = row0 + ai * HALF + m * 16; const float rs = rsc ? rsc[row - rbase] : rstd[row];
.LBB0_169:
	s_andn2_b64 vcc, exec, s[0:1]
	s_cbranch_vccnz .LBB0_171
	s_waitcnt vmcnt(0)
	v_mov_b32_e32 v102, v232

;     __device__ __forceinline__ void operator()(const f32x4 (&acc)[2][2][4][2], const Unit& u, int wr, int wc, int fr, int fq) const {
;     ...
;                 for (int m = 0; m < 4; ++m) {
;                     const int row = row0 + ai * HALF + m * 16; const float rs = rsc ? rsc[row - rbase] : rstd[row];
.LBB0_182:
	s_andn2_b64 vcc, exec, s[0:1]
	s_cbranch_vccnz .LBB0_184
	s_waitcnt vmcnt(0)
	v_mov_b32_e32 v94, v233

;     __device__ __forceinline__ void operator()(const f32x4 (&acc)[2][2][4][2], const Unit& u, int wr, int wc, int fr, int fq) const {
;     ...
;                 for (int m = 0; m < 4; ++m) {
;                     const int row = row0 + ai * HALF + m * 16; const float rs = rsc ? rsc[row - rbase] : rstd[row];
.LBB0_195:
	s_andn2_b64 vcc, exec, s[0:1]
	s_cbranch_vccnz .LBB0_197
	s_waitcnt vmcnt(0)
	v_mov_b32_e32 v86, v234

;     __device__ __forceinline__ void operator()(const f32x4 (&acc)[2][2][4][2], const Unit& u, int wr, int wc, int fr, int fq) const {
;     ...
;                 for (int m = 0; m < 4; ++m) {
;                     const int row = row0 + ai * HALF + m * 16; const float rs = rsc ? rsc[row - rbase] : rstd[row];
.LBB0_208:
	s_andn2_b64 vcc, exec, s[0:1]
	s_cbranch_vccnz .LBB0_210
	s_waitcnt vmcnt(0)
	v_mov_b32_e32 v78, v235

;     __device__ __forceinline__ void operator()(const f32x4 (&acc)[2][2][4][2], const Unit& u, int wr, int wc, int fr, int fq) const {
;     ...
;                 for (int m = 0; m < 4; ++m) {
;                     const int row = row0 + ai * HALF + m * 16; const float rs = rsc ? rsc[row - rbase] : rstd[row];
.LBB0_222:
	s_waitcnt vmcnt(0)
	ds_read_b32 v228, v165
	ds_read_b32 v229, v165 offset:64
	ds_read_b32 v230, v165 offset:128
	ds_read_b32 v231, v165 offset:192
	ds_read_b32 v232, v165 offset:512
	ds_read_b32 v233, v165 offset:576
	ds_read_b32 v234, v165 offset:640
	ds_read_b32 v235, v165 offset:704
	s_waitcnt lgkmcnt(0)
	v_mov_b32_e32 v68, v228

;     __device__ __forceinline__ void operator()(const f32x4 (&acc)[2][2][4][2], const Unit& u, int wr, int wc, int fr, int fq) const {
;     ...
;                 for (int m = 0; m < 4; ++m) {
;                     const int row = row0 + ai * HALF + m * 16; const float rs = rsc ? rsc[row - rbase] : rstd[row];
.LBB0_234:
	s_andn2_b64 vcc, exec, s[0:1]
	s_cbranch_vccnz .LBB0_236
	s_waitcnt vmcnt(0)
	v_mov_b32_e32 v58, v229

;     __device__ __forceinline__ void operator()(const f32x4 (&acc)[2][2][4][2], const Unit& u, int wr, int wc, int fr, int fq) const {
;     ...
;                 for (int m = 0; m < 4; ++m) {
;                     const int row = row0 + ai * HALF + m * 16; const float rs = rsc ? rsc[row - rbase] : rstd[row];
.LBB0_247:
	s_andn2_b64 vcc, exec, s[0:1]
	s_cbranch_vccnz .LBB0_249
	s_waitcnt vmcnt(0)
	v_mov_b32_e32 v50, v230

;     __device__ __forceinline__ void operator()(const f32x4 (&acc)[2][2][4][2], const Unit& u, int wr, int wc, int fr, int fq) const {
;     ...
;                 for (int m = 0; m < 4; ++m) {
;                     const int row = row0 + ai * HALF + m * 16; const float rs = rsc ? rsc[row - rbase] : rstd[row];
.LBB0_260:
	s_andn2_b64 vcc, exec, s[0:1]
	s_cbranch_vccnz .LBB0_262
	s_waitcnt vmcnt(0)
	v_mov_b32_e32 v42, v231

;     __device__ __forceinline__ void operator()(const f32x4 (&acc)[2][2][4][2], const Unit& u, int wr, int wc, int fr, int fq) const {
;     ...
;                 for (int m = 0; m < 4; ++m) {
;                     const int row = row0 + ai * HALF + m * 16; const float rs = rsc ? rsc[row - rbase] : rstd[row];
.LBB0_273:
	s_andn2_b64 vcc, exec, s[0:1]
	s_cbranch_vccnz .LBB0_275
	s_waitcnt vmcnt(0)
	v_mov_b32_e32 v34, v232

;     __device__ __forceinline__ void operator()(const f32x4 (&acc)[2][2][4][2], const Unit& u, int wr, int wc, int fr, int fq) const {
;     ...
;                 for (int m = 0; m < 4; ++m) {
;                     const int row = row0 + ai * HALF + m * 16; const float rs = rsc ? rsc[row - rbase] : rstd[row];
.LBB0_286:
	s_andn2_b64 vcc, exec, s[0:1]
	s_cbranch_vccnz .LBB0_288
	s_waitcnt vmcnt(0)
	v_mov_b32_e32 v26, v233

;     __device__ __forceinline__ void operator()(const f32x4 (&acc)[2][2][4][2], const Unit& u, int wr, int wc, int fr, int fq) const {
;     ...
;                 for (int m = 0; m < 4; ++m) {
;                     const int row = row0 + ai * HALF + m * 16; const float rs = rsc ? rsc[row - rbase] : rstd[row];
.LBB0_299:
	s_andn2_b64 vcc, exec, s[0:1]
	s_cbranch_vccnz .LBB0_301
	s_waitcnt vmcnt(0)
	v_mov_b32_e32 v18, v234

;     __device__ __forceinline__ void operator()(const f32x4 (&acc)[2][2][4][2], const Unit& u, int wr, int wc, int fr, int fq) const {
;     ...
;                 for (int m = 0; m < 4; ++m) {
;                     const int row = row0 + ai * HALF + m * 16; const float rs = rsc ? rsc[row - rbase] : rstd[row];
.LBB0_312:
	s_andn2_b64 vcc, exec, s[0:1]
	s_cbranch_vccnz .LBB0_314
	s_waitcnt vmcnt(0)
	v_mov_b32_e32 v10, v235

; #define LAS __attribute__((address_space(3)))
; __device__ __forceinline__ unsigned pk2(float lo, float hi) { return f2bf(lo) | (f2bf(hi) << 16); }
; __device__ __forceinline__ void attn_item(Frame& F, int item) {
;     ...
;         const int key = tid >> 1, half = tid & 1, pos = p0 - 128 + key;
;         v4u kw[4], vw[4];
;         if (pos >= 0) {
;             const v4u* kr = (const v4u*)(F.PROJ + ((size_t)b * SEQ + pos) * PW + C_AK + kvh * 64 + half * 32);
;             const v4u* vr = (const v4u*)(F.PROJ + ((size_t)b * SEQ + pos) * PW + C_AV + kvh * 64 + half * 32);
; #pragma unroll
;             for (int i = 0; i < 4; ++i) { kw[i] = kr[i]; vw[i] = vr[i]; }
;         } else {
; #pragma unroll
;             for (int i = 0; i < 4; ++i) { kw[i] = (v4u){0u, 0u, 0u, 0u}; vw[i] = (v4u){0u, 0u, 0u, 0u}; }
;         }
;         float ss = 0.f;
; #pragma unroll
;         for (int i = 0; i < 4; ++i)
; #pragma unroll
;             for (int j = 0; j < 4; ++j) { const float a = bflo(kw[i][j]), c = bfhi(kw[i][j]); ss += a * a + c * c; }
;         ss += __shfl_xor(ss, 1);
;         const float rs = __builtin_amdgcn_rsqf(ss * (1.0f / 64.0f) + EPS);
; #pragma unroll
;         for (int i = 0; i < 4; ++i) {
;             const f32x4 g0 = *(const f32x4*)(F.kg + half * 32 + 8 * i), g1 = *(const f32x4*)(F.kg + half * 32 + 8 * i + 4);
;             v4u o;
;             o.x = pk2(bflo(kw[i][0]) * rs * g0[0], bfhi(kw[i][0]) * rs * g0[1]); o.y = pk2(bflo(kw[i][1]) * rs * g0[2], bfhi(kw[i][1]) * rs * g0[3]);
;             o.z = pk2(bflo(kw[i][2]) * rs * g1[0], bfhi(kw[i][2]) * rs * g1[1]); o.w = pk2(bflo(kw[i][3]) * rs * g1[2], bfhi(kw[i][3]) * rs * g1[3]);
;             *(LAS v4u*)(Ks + key * KS_STRIDE + half * 32 + 8 * i) = o;
; #pragma unroll
;             for (int j = 0; j < 4; ++j) {
;                 Vt[(half * 32 + 8 * i + 2 * j) * VT2_STRIDE + key] = (bf16)(vw[i][j] & 0xffffu);
;                 Vt[(half * 32 + 8 * i + 2 * j + 1) * VT2_STRIDE + key] = (bf16)(vw[i][j] >> 16);
;             }
;         }
.LBB0_488:
	s_or_b64 exec, exec, s[78:79]
	global_load_dwordx4 v[56:59], v[194:195], off
	global_load_dwordx4 v[60:63], v[194:195], off offset:16
	global_load_dwordx4 v[22:25], v[194:195], off offset:48
	global_load_dwordx4 v[26:29], v[194:195], off offset:32
	s_waitcnt vmcnt(10)
	v_lshlrev_b32_e32 v55, 16, v39
	v_lshlrev_b32_e32 v54, 16, v38
	v_and_b32_e32 v53, 0xffff0000, v39
	v_and_b32_e32 v52, 0xffff0000, v38
	v_lshlrev_b32_e32 v51, 16, v41
	v_lshlrev_b32_e32 v50, 16, v40
	v_and_b32_e32 v49, 0xffff0000, v41
	v_and_b32_e32 v48, 0xffff0000, v40
	s_waitcnt vmcnt(7)
	v_lshlrev_b32_e32 v41, 16, v45
	v_lshlrev_b32_e32 v40, 16, v44
	v_and_b32_e32 v39, 0xffff0000, v45
	v_and_b32_e32 v38, 0xffff0000, v44
	v_lshlrev_b32_e32 v45, 16, v35
	v_lshlrev_b32_e32 v44, 16, v34
	v_and_b32_e32 v35, 0xffff0000, v35
	v_and_b32_e32 v34, 0xffff0000, v34
	v_lshlrev_b32_e32 v65, 16, v37
	v_lshlrev_b32_e32 v64, 16, v36
	v_and_b32_e32 v37, 0xffff0000, v37
	v_and_b32_e32 v36, 0xffff0000, v36
	v_pk_mul_f32 v[78:79], v[34:35], v[34:35]
	v_pk_mul_f32 v[80:81], v[36:37], v[36:37]
	v_pk_fma_f32 v[78:79], v[44:45], v[44:45], v[78:79]
	v_and_b32_e32 v69, 0xffff0000, v31
	v_and_b32_e32 v68, 0xffff0000, v30
	v_pk_fma_f32 v[80:81], v[64:65], v[64:65], v[80:81]
	v_add_f32_e32 v1, v78, v79
	v_lshlrev_b32_e32 v67, 16, v31
	v_lshlrev_b32_e32 v66, 16, v30
	v_pk_mul_f32 v[82:83], v[68:69], v[68:69]
	v_add_f32_e32 v1, v80, v1
	s_waitcnt vmcnt(4)
	v_and_b32_e32 v73, 0xffff0000, v33
	v_and_b32_e32 v72, 0xffff0000, v32
	v_pk_fma_f32 v[82:83], v[66:67], v[66:67], v[82:83]
	v_add_f32_e32 v1, v81, v1
	v_lshlrev_b32_e32 v71, 16, v33
	v_lshlrev_b32_e32 v70, 16, v32
	v_pk_mul_f32 v[84:85], v[72:73], v[72:73]
	v_add_f32_e32 v1, v82, v1
	v_pk_fma_f32 v[84:85], v[70:71], v[70:71], v[84:85]
	v_add_f32_e32 v1, v83, v1
	v_pk_mul_f32 v[30:31], v[52:53], v[52:53]
	v_add_f32_e32 v1, v84, v1
	v_pk_fma_f32 v[30:31], v[54:55], v[54:55], v[30:31]
	v_add_f32_e32 v1, v85, v1
	v_pk_mul_f32 v[32:33], v[48:49], v[48:49]
	v_add_f32_e32 v1, v30, v1
	v_lshlrev_b32_e32 v47, 16, v43
	v_lshlrev_b32_e32 v46, 16, v42
	v_and_b32_e32 v43, 0xffff0000, v43
	v_and_b32_e32 v42, 0xffff0000, v42
	v_pk_fma_f32 v[32:33], v[50:51], v[50:51], v[32:33]
	v_add_f32_e32 v1, v31, v1
	v_pk_mul_f32 v[74:75], v[42:43], v[42:43]
	v_add_f32_e32 v1, v32, v1
	v_pk_fma_f32 v[74:75], v[46:47], v[46:47], v[74:75]
	v_add_f32_e32 v1, v33, v1
	v_pk_mul_f32 v[76:77], v[38:39], v[38:39]
	v_add_f32_e32 v1, v74, v1
	v_pk_fma_f32 v[76:77], v[40:41], v[40:41], v[76:77]
	v_add_f32_e32 v1, v75, v1
	v_add_f32_e32 v1, v76, v1
	v_add_f32_e32 v1, v77, v1
	ds_bpermute_b32 v5, v187, v1
	s_and_b32 s0, s81, 1
	s_lshl_b32 s78, s0, 4
	s_add_u32 s78, s50, s78
	s_addc_u32 s79, s51, 0
	s_waitcnt lgkmcnt(0)
	v_add_f32_e32 v1, v1, v5
	v_fmamk_f32 v1, v1, 0x3c800000, v213
	s_and_b32 s81, s84, 15
	s_lshl_b32 s0, s0, 9
	s_cmp_eq_u32 s80, 0
	v_lshl_or_b32 v158, s81, 7, v209
	s_cselect_b64 s[80:81], -1, 0
	s_add_u32 s82, s33, s82
	v_mov_b32_e32 v159, v4
	s_waitcnt vmcnt(3)
	v_mov_b32_e32 v30, v56
	s_waitcnt vmcnt(2)
	v_mov_b32_e32 v32, v60
	v_rsq_f32_e32 v60, v1
	v_mov_b32_e32 v31, v58
	s_waitcnt vmcnt(0)
	v_mov_b32_e32 v74, v26
	v_mov_b32_e32 v75, v28
	v_mov_b32_e32 v28, v27
	v_pk_mul_f32 v[26:27], v[60:61], v[44:45] op_sel_hi:[0,1]
	v_mov_b32_e32 v58, v57
	v_pk_mul_f32 v[26:27], v[30:31], v[26:27]
	v_pk_mul_f32 v[30:31], v[60:61], v[34:35] op_sel_hi:[0,1]
	v_mov_b32_e32 v33, v62
	v_pk_mul_f32 v[44:45], v[58:59], v[30:31]
	v_pk_mul_f32 v[30:31], v[60:61], v[64:65] op_sel_hi:[0,1]
	v_mov_b32_e32 v62, v61
	v_pk_mul_f32 v[56:57], v[32:33], v[30:31]
	v_pk_mul_f32 v[30:31], v[60:61], v[36:37] op_sel_hi:[0,1]
	v_pk_mul_f32 v[58:59], v[62:63], v[30:31]
	v_bfe_u32 v1, v59, 16, 1
	v_bfe_u32 v5, v58, 16, 1
	global_load_dwordx4 v[30:33], v[194:195], off offset:80
	global_load_dwordx4 v[34:37], v[194:195], off offset:64
	v_add3_u32 v5, v58, v5, s66
	v_add3_u32 v1, v59, v1, s66
	v_bfe_u32 v61, v56, 16, 1
	v_bfe_u32 v62, v57, 16, 1
	v_add3_u32 v57, v57, v62, s66
	v_add3_u32 v56, v56, v61, s66
	v_lshrrev_b32_e32 v56, 16, v56
	v_lshrrev_b32_e32 v57, 16, v57
	v_and_or_b32 v59, v1, s63, v57
	v_and_or_b32 v58, v5, s63, v56
	v_cvt_pk_bf16_f32 v57, v27, v45
	v_cvt_pk_bf16_f32 v56, v26, v44
	ds_write_b128 v211, v[56:59]
	ds_write_b16 v212, v18 offset:36864
	ds_write_b16_d16_hi v212, v18 offset:37392
	ds_write_b16 v212, v19 offset:37920
	ds_write_b16_d16_hi v212, v19 offset:38448
	ds_write_b16 v212, v20 offset:38976
	ds_write_b16_d16_hi v212, v20 offset:39504
	ds_write_b16 v212, v21 offset:40032
	ds_write_b16_d16_hi v212, v21 offset:40560
	v_pk_mul_f32 v[18:19], v[60:61], v[66:67] op_sel_hi:[0,1]
	v_pk_mul_f32 v[26:27], v[74:75], v[18:19]
	v_pk_mul_f32 v[18:19], v[60:61], v[68:69] op_sel_hi:[0,1]
	v_pk_mul_f32 v[28:29], v[28:29], v[18:19]
	v_pk_mul_f32 v[18:19], v[60:61], v[70:71] op_sel_hi:[0,1]
	v_mov_b32_e32 v20, v22
	v_mov_b32_e32 v21, v24
	v_pk_mul_f32 v[44:45], v[20:21], v[18:19]
	v_pk_mul_f32 v[18:19], v[60:61], v[72:73] op_sel_hi:[0,1]
	v_mov_b32_e32 v24, v23
	v_pk_mul_f32 v[56:57], v[24:25], v[18:19]
	global_load_dwordx4 v[18:21], v[194:195], off offset:112
	global_load_dwordx4 v[22:25], v[194:195], off offset:96
	v_bfe_u32 v58, v29, 16, 1
	v_bfe_u32 v59, v28, 16, 1
	v_add3_u32 v59, v28, v59, s66
	v_add3_u32 v58, v29, v58, s66
	v_bfe_u32 v28, v26, 16, 1
	v_bfe_u32 v29, v27, 16, 1
	v_add3_u32 v27, v27, v29, s66
	v_add3_u32 v26, v26, v28, s66
	v_lshrrev_b32_e32 v26, 16, v26
	v_lshrrev_b32_e32 v27, 16, v27
	v_cvt_pk_bf16_f32 v29, v45, v57
	v_cvt_pk_bf16_f32 v28, v44, v56
	v_and_or_b32 v27, v58, s63, v27
	v_and_or_b32 v26, v59, s63, v26
	ds_write_b128 v211, v[26:29] offset:16
	ds_write_b16 v212, v14 offset:41088
	ds_write_b16_d16_hi v212, v14 offset:41616
	ds_write_b16 v212, v15 offset:42144
	ds_write_b16_d16_hi v212, v15 offset:42672
	ds_write_b16 v212, v16 offset:43200
	ds_write_b16_d16_hi v212, v16 offset:43728
	ds_write_b16 v212, v17 offset:44256
	ds_write_b16_d16_hi v212, v17 offset:44784
	v_pk_mul_f32 v[14:15], v[60:61], v[54:55] op_sel_hi:[0,1]
	v_pk_mul_f32 v[26:27], v[60:61], v[50:51] op_sel_hi:[0,1]
	s_addc_u32 s83, 0, s83
	v_mov_b32_e32 v3, v4
	v_mov_b32_e32 v2, s0
	v_lshl_add_u64 v[158:159], s[82:83], 0, v[158:159]
	v_mad_u64_u32 v[2:3], s[82:83], v158, s60, v[2:3]
	v_mad_i32_i24 v3, v159, s60, v3
	v_lshl_add_u64 v[202:203], v[196:197], 0, v[2:3]
	v_lshlrev_b64 v[2:3], 11, v[158:159]
	v_or_b32_e32 v2, s0, v2
	v_mov_b32_e32 v116, v4
	v_mov_b32_e32 v117, v4
	v_mov_b32_e32 v156, v4
	v_mov_b32_e32 v157, v4
	v_lshl_add_u64 v[204:205], v[198:199], 0, v[2:3]
	s_mov_b64 s[82:83], 0
	s_waitcnt vmcnt(3)
; #define LAS __attribute__((address_space(3)))
; __device__ __forceinline__ unsigned pk2(float lo, float hi) { return f2bf(lo) | (f2bf(hi) << 16); }
; __device__ __forceinline__ void attn_item(Frame& F, int item) {
;     ...
; #pragma unroll
;         for (int i = 0; i < 4; ++i) {
;             const f32x4 g0 = *(const f32x4*)(F.kg + half * 32 + 8 * i), g1 = *(const f32x4*)(F.kg + half * 32 + 8 * i + 4);
;             v4u o;
;             o.x = pk2(bflo(kw[i][0]) * rs * g0[0], bfhi(kw[i][0]) * rs * g0[1]); o.y = pk2(bflo(kw[i][1]) * rs * g0[2], bfhi(kw[i][1]) * rs * g0[3]);
;             o.z = pk2(bflo(kw[i][2]) * rs * g1[0], bfhi(kw[i][2]) * rs * g1[1]); o.w = pk2(bflo(kw[i][3]) * rs * g1[2], bfhi(kw[i][3]) * rs * g1[3]);
;             *(LAS v4u*)(Ks + key * KS_STRIDE + half * 32 + 8 * i) = o;
; #pragma unroll
;             for (int j = 0; j < 4; ++j) {
;                 Vt[(half * 32 + 8 * i + 2 * j) * VT2_STRIDE + key] = (bf16)(vw[i][j] & 0xffffu);
;                 Vt[(half * 32 + 8 * i + 2 * j + 1) * VT2_STRIDE + key] = (bf16)(vw[i][j] >> 16);
;             }
;         }
;     }
;     __syncthreads();
;     bf16x8 kf[9][2];
; #pragma unroll
;     for (int kt = 0; kt < 9; ++kt)
; #pragma unroll
;         for (int ks = 0; ks < 2; ++ks) kf[kt][ks] = *(const LAS bf16x8*)(Ks + (16 * w + 16 * kt + l15) * KS_STRIDE + 32 * ks + 8 * quad);
;     ...
;             const LAS bf16* vrow = Vt + (16 * dt + l15) * VT2_STRIDE + 16 * w + 4 * quad;
; #pragma unroll
;             for (int kk = 0; kk < 5; ++kk) {
;                 const v2u lo = *(const LAS v2u*)(vrow + 32 * kk);
;                 v2u hi = (v2u){0u, 0u}; if (kk < 4) hi = *(const LAS v2u*)(vrow + 32 * kk + 16);
	v_mov_b32_e32 v28, v30
	s_waitcnt vmcnt(2)
	v_mov_b32_e32 v16, v34
	v_mov_b32_e32 v17, v36
	v_mov_b32_e32 v29, v32
	v_pk_mul_f32 v[14:15], v[14:15], v[16:17]
	v_pk_mul_f32 v[16:17], v[60:61], v[52:53] op_sel_hi:[0,1]
	v_mov_b32_e32 v36, v35
	v_pk_mul_f32 v[26:27], v[26:27], v[28:29]
	v_pk_mul_f32 v[28:29], v[60:61], v[48:49] op_sel_hi:[0,1]
	v_mov_b32_e32 v32, v31
	v_pk_mul_f32 v[16:17], v[16:17], v[36:37]
	v_pk_mul_f32 v[28:29], v[28:29], v[32:33]
	v_bfe_u32 v30, v17, 16, 1
	v_bfe_u32 v31, v16, 16, 1
	v_add3_u32 v31, v16, v31, s66
	v_add3_u32 v30, v17, v30, s66
	v_bfe_u32 v16, v14, 16, 1
	v_bfe_u32 v17, v15, 16, 1
	v_add3_u32 v15, v15, v17, s66
	v_add3_u32 v14, v14, v16, s66
	v_lshrrev_b32_e32 v14, 16, v14
	v_lshrrev_b32_e32 v15, 16, v15
	v_cvt_pk_bf16_f32 v17, v27, v29
	v_cvt_pk_bf16_f32 v16, v26, v28
	v_and_or_b32 v15, v30, s63, v15
	v_and_or_b32 v14, v31, s63, v14
	ds_write_b128 v211, v[14:17] offset:32
	ds_write_b16 v212, v10 offset:45312
	ds_write_b16_d16_hi v212, v10 offset:45840
	ds_write_b16 v212, v11 offset:46368
	ds_write_b16_d16_hi v212, v11 offset:46896
	ds_write_b16 v212, v12 offset:47424
	ds_write_b16_d16_hi v212, v12 offset:47952
	ds_write_b16 v212, v13 offset:48480
	ds_write_b16_d16_hi v212, v13 offset:49008
	v_pk_mul_f32 v[10:11], v[60:61], v[46:47] op_sel_hi:[0,1]
	s_waitcnt vmcnt(0)
	v_mov_b32_e32 v12, v22
	v_mov_b32_e32 v13, v24
	v_pk_mul_f32 v[14:15], v[60:61], v[40:41] op_sel_hi:[0,1]
	v_mov_b32_e32 v16, v18
	v_mov_b32_e32 v17, v20
	v_pk_mul_f32 v[10:11], v[10:11], v[12:13]
	v_pk_mul_f32 v[12:13], v[60:61], v[42:43] op_sel_hi:[0,1]
	v_mov_b32_e32 v24, v23
	v_pk_mul_f32 v[14:15], v[14:15], v[16:17]
	v_pk_mul_f32 v[16:17], v[60:61], v[38:39] op_sel_hi:[0,1]
	v_mov_b32_e32 v20, v19
	v_pk_mul_f32 v[12:13], v[12:13], v[24:25]
	v_pk_mul_f32 v[16:17], v[16:17], v[20:21]
	v_bfe_u32 v18, v13, 16, 1
	v_bfe_u32 v19, v12, 16, 1
	v_add3_u32 v19, v12, v19, s66
	v_add3_u32 v18, v13, v18, s66
	v_bfe_u32 v12, v10, 16, 1
	v_bfe_u32 v13, v11, 16, 1
	v_add3_u32 v11, v11, v13, s66
	v_add3_u32 v10, v10, v12, s66
	v_lshrrev_b32_e32 v10, 16, v10
	v_lshrrev_b32_e32 v11, 16, v11
	v_cvt_pk_bf16_f32 v13, v15, v17
	v_cvt_pk_bf16_f32 v12, v14, v16
	v_and_or_b32 v11, v18, s63, v11
	v_and_or_b32 v10, v19, s63, v10
	ds_write_b128 v211, v[10:13] offset:48
	ds_write_b16 v212, v6 offset:49536
	ds_write_b16_d16_hi v212, v6 offset:50064
	ds_write_b16 v212, v7 offset:50592
	ds_write_b16_d16_hi v212, v7 offset:51120
	ds_write_b16 v212, v8 offset:51648
	ds_write_b16_d16_hi v212, v8 offset:52176
	ds_write_b16 v212, v9 offset:52704
	ds_write_b16_d16_hi v212, v9 offset:53232
	s_waitcnt lgkmcnt(0)
	s_barrier
	ds_read_b128 v[6:9], v214
	ds_read_b128 v[10:13], v214 offset:64
	ds_read_b128 v[14:17], v215
	ds_read_b128 v[18:21], v215 offset:64
	ds_read_b128 v[22:25], v216
	ds_read_b128 v[26:29], v216 offset:64
	ds_read_b128 v[30:33], v217
	ds_read_b128 v[34:37], v217 offset:64
	ds_read_b128 v[38:41], v218
	ds_read_b128 v[42:45], v218 offset:64
	ds_read_b128 v[46:49], v219
	ds_read_b128 v[50:53], v219 offset:64
	ds_read_b128 v[54:57], v220
	ds_read_b128 v[58:61], v220 offset:64
	ds_read_b128 v[62:65], v221
	ds_read_b128 v[66:69], v221 offset:64
	ds_read_b128 v[70:73], v222
	ds_read_b128 v[74:77], v222 offset:64
	v_add_u32_e32 v1, 0x9000, v223
	v_add_u32_e32 v5, 0x100, v223
	ds_read2st64_b64 v[96:99], v5 offset0:72 offset1:88
	ds_read2_b64 v[78:81], v1 offset1:4
	ds_read2_b64 v[82:85], v1 offset0:8 offset1:12
	ds_read2_b64 v[86:89], v1 offset0:16 offset1:20
	ds_read2_b64 v[90:93], v1 offset0:24 offset1:28
	v_add_u32_e32 v1, 0xb000, v223
	ds_read2_b64 v[100:103], v1 offset0:36 offset1:40
	ds_read2_b64 v[104:107], v1 offset0:44 offset1:48
	ds_read2_b64 v[108:111], v1 offset0:52 offset1:56
	ds_read2_b64 v[112:115], v1 offset0:60 offset1:64
	v_add_u32_e32 v1, 0xd000, v223
	ds_read2st64_b64 v[136:139], v5 offset0:105 offset1:121
	ds_read2_b64 v[118:121], v1 offset0:64 offset1:68
	ds_read2_b64 v[122:125], v1 offset0:72 offset1:76
	ds_read2_b64 v[126:129], v1 offset0:80 offset1:84
	ds_read2_b64 v[130:133], v1 offset0:88 offset1:92
	v_add_u32_e32 v1, 0xf000, v223
	ds_read2_b64 v[140:143], v1 offset0:100 offset1:104
	ds_read2_b64 v[144:147], v1 offset0:108 offset1:112
	ds_read2_b64 v[148:151], v1 offset0:116 offset1:120
	ds_read2_b64 v[152:155], v1 offset0:124 offset1:128
	s_waitcnt lgkmcnt(14)
	v_mov_b32_e32 v94, v96
	v_mov_b32_e32 v95, v97
	v_mov_b32_e32 v96, v4
	v_mov_b32_e32 v97, v4
	s_waitcnt lgkmcnt(8)
	v_mov_b32_e32 v134, v136
	v_mov_b32_e32 v135, v137
	v_mov_b32_e32 v136, v4
	v_mov_b32_e32 v137, v4
	s_branch .LBB0_490
; __device__ __forceinline__ void attn_item(Frame& F, int item) {
;     ...
; #pragma unroll
;         for (int r = 0; r < 4; ++r) { if (!(l15 < 4 * quad + r)) sc[0][r] = NEG; if (!(l15 >= 4 * quad + r)) sc[8][r] = NEG; }
;         if (qb == 0) {
; #pragma unroll
;             for (int kt = 0; kt < 9; ++kt)
; #pragma unroll
;                 for (int r = 0; r < 4; ++r) if (16 * w + 16 * kt + 4 * quad + r < 128) sc[kt][r] = NEG;
;         }
;         const float sink = F.sinks[qh];
;         float m = sink;
; #pragma unroll
;         for (int kt = 0; kt < 9; ++kt)
; #pragma unroll
;             for (int r = 0; r < 4; ++r) m = fmaxf(m, sc[kt][r]);
;         m = fmaxf(m, __shfl_xor(m, 16)); m = fmaxf(m, __shfl_xor(m, 32));
;         float l = 0.f;
; #pragma unroll
;         for (int kt = 0; kt < 9; ++kt)
; #pragma unroll
;             for (int r = 0; r < 4; ++r) { const float p = __expf(sc[kt][r] - m); sc[kt][r] = p; l += p; }
;         l += __shfl_xor(l, 16); l += __shfl_xor(l, 32);
;         l += __expf(sink - m);
;         const float il = __builtin_amdgcn_rcpf(l);
;         bf16x8 pf[5];
; #pragma unroll
;         for (int kk = 0; kk < 4; ++kk) pf[kk] = pack8(sc[2 * kk], sc[2 * kk + 1]);
;         pf[4] = pack8(sc[8], (f32x4){0.f, 0.f, 0.f, 0.f});
.LBB0_489:
	global_load_dword v5, v4, s[78:79]
	s_and_b64 vcc, s[10:11], s[8:9]
	s_nop 4
	v_cndmask_b32_e32 v190, v190, v224, vcc
	s_and_b64 vcc, vcc, s[6:7]
	v_cndmask_b32_e32 v189, v189, v224, vcc
	s_and_b64 vcc, vcc, s[4:5]
	v_cndmask_b32_e32 v188, v188, v224, vcc
	v_cndmask_b32_e64 v191, v191, v224, s[10:11]
	s_waitcnt vmcnt(0)
	v_max3_f32 v201, v5, v186, v1
	v_max3_f32 v201, v201, v2, v3
	v_max3_f32 v201, v201, v182, v183
	v_max3_f32 v201, v201, v184, v185
	v_max3_f32 v201, v201, v178, v179
	v_max3_f32 v201, v201, v180, v181
	v_max3_f32 v201, v201, v174, v175
	v_max3_f32 v201, v201, v176, v177
	v_max3_f32 v201, v201, v170, v171
	v_max3_f32 v201, v201, v172, v173
	v_max3_f32 v201, v201, v166, v167
	v_max3_f32 v201, v201, v168, v169
	v_max3_f32 v201, v201, v162, v163
	v_max3_f32 v201, v201, v164, v165
	v_max3_f32 v201, v201, v158, v159
	v_max3_f32 v201, v201, v160, v161
	v_max3_f32 v201, v201, v188, v189
	v_max3_f32 v201, v201, v190, v191
	ds_bpermute_b32 v226, v207, v201
	s_waitcnt lgkmcnt(0)
	v_max_f32_e32 v226, v226, v226
	v_max_f32_e32 v201, v201, v226
	ds_bpermute_b32 v226, v208, v201
	s_waitcnt lgkmcnt(0)
	v_max_f32_e32 v226, v226, v226
	v_max_f32_e32 v201, v201, v226
	v_sub_f32_e32 v186, v186, v201
	v_sub_f32_e32 v1, v1, v201
	v_mul_f32_e32 v186, 0x3fb8aa3b, v186
	v_sub_f32_e32 v2, v2, v201
	v_mul_f32_e32 v1, 0x3fb8aa3b, v1
	v_exp_f32_e32 v186, v186
	v_sub_f32_e32 v3, v3, v201
	v_mul_f32_e32 v2, 0x3fb8aa3b, v2
	v_exp_f32_e32 v1, v1
	v_sub_f32_e32 v182, v182, v201
	v_sub_f32_e32 v162, v162, v201
	v_mul_f32_e32 v3, 0x3fb8aa3b, v3
	v_exp_f32_e32 v2, v2
	v_sub_f32_e32 v183, v183, v201
	v_mul_f32_e32 v182, 0x3fb8aa3b, v182
	v_mul_f32_e32 v162, 0x3fb8aa3b, v162
	v_exp_f32_e32 v3, v3
	v_sub_f32_e32 v184, v184, v201
	v_mul_f32_e32 v183, 0x3fb8aa3b, v183
	v_exp_f32_e32 v182, v182
	v_exp_f32_e32 v230, v162
	v_add_f32_e32 v162, 0, v186
	v_sub_f32_e32 v185, v185, v201
	v_mul_f32_e32 v184, 0x3fb8aa3b, v184
	v_exp_f32_e32 v183, v183
	v_add_f32_e32 v162, v1, v162
	v_sub_f32_e32 v178, v178, v201
	v_mul_f32_e32 v185, 0x3fb8aa3b, v185
	v_exp_f32_e32 v184, v184
	v_add_f32_e32 v162, v2, v162
	v_sub_f32_e32 v179, v179, v201
	v_mul_f32_e32 v178, 0x3fb8aa3b, v178
	v_exp_f32_e32 v185, v185
	v_add_f32_e32 v162, v3, v162
	v_sub_f32_e32 v180, v180, v201
	v_mul_f32_e32 v179, 0x3fb8aa3b, v179
	v_exp_f32_e32 v178, v178
	v_add_f32_e32 v162, v182, v162
	v_sub_f32_e32 v181, v181, v201
	v_mul_f32_e32 v180, 0x3fb8aa3b, v180
	v_exp_f32_e32 v179, v179
	v_add_f32_e32 v162, v183, v162
	v_sub_f32_e32 v174, v174, v201
	v_mul_f32_e32 v181, 0x3fb8aa3b, v181
	v_exp_f32_e32 v180, v180
	v_add_f32_e32 v162, v184, v162
	v_sub_f32_e32 v175, v175, v201
	v_mul_f32_e32 v174, 0x3fb8aa3b, v174
	v_exp_f32_e32 v181, v181
	v_add_f32_e32 v162, v185, v162
	v_sub_f32_e32 v176, v176, v201
	v_mul_f32_e32 v175, 0x3fb8aa3b, v175
	v_exp_f32_e32 v174, v174
	v_add_f32_e32 v162, v178, v162
	v_sub_f32_e32 v177, v177, v201
	v_mul_f32_e32 v176, 0x3fb8aa3b, v176
	v_exp_f32_e32 v175, v175
	v_add_f32_e32 v162, v179, v162
	v_sub_f32_e32 v170, v170, v201
	v_mul_f32_e32 v177, 0x3fb8aa3b, v177
	v_exp_f32_e32 v176, v176
	v_add_f32_e32 v162, v180, v162
	v_sub_f32_e32 v171, v171, v201
	v_mul_f32_e32 v170, 0x3fb8aa3b, v170
	v_exp_f32_e32 v177, v177
	v_add_f32_e32 v162, v181, v162
	v_sub_f32_e32 v172, v172, v201
	v_mul_f32_e32 v171, 0x3fb8aa3b, v171
	v_exp_f32_e32 v170, v170
	v_add_f32_e32 v162, v174, v162
	v_sub_f32_e32 v173, v173, v201
	v_mul_f32_e32 v172, 0x3fb8aa3b, v172
	v_exp_f32_e32 v171, v171
	v_add_f32_e32 v162, v175, v162
	v_sub_f32_e32 v166, v166, v201
	v_mul_f32_e32 v173, 0x3fb8aa3b, v173
	v_exp_f32_e32 v172, v172
	v_add_f32_e32 v162, v176, v162
	v_sub_f32_e32 v167, v167, v201
	v_mul_f32_e32 v166, 0x3fb8aa3b, v166
	v_exp_f32_e32 v173, v173
	v_add_f32_e32 v162, v177, v162
	v_sub_f32_e32 v168, v168, v201
	v_mul_f32_e32 v167, 0x3fb8aa3b, v167
	v_exp_f32_e32 v226, v166
	v_add_f32_e32 v162, v170, v162
	v_sub_f32_e32 v169, v169, v201
	v_mul_f32_e32 v168, 0x3fb8aa3b, v168
	v_exp_f32_e32 v227, v167
	v_add_f32_e32 v162, v171, v162
	v_mul_f32_e32 v169, 0x3fb8aa3b, v169
	v_exp_f32_e32 v228, v168
	v_add_f32_e32 v162, v172, v162
	v_sub_f32_e32 v163, v163, v201
	v_sub_f32_e32 v158, v158, v201
	v_exp_f32_e32 v229, v169
	v_add_f32_e32 v162, v173, v162
	v_sub_f32_e32 v164, v164, v201
	v_mul_f32_e32 v163, 0x3fb8aa3b, v163
	v_mul_f32_e32 v158, 0x3fb8aa3b, v158
	v_add_f32_e32 v162, v226, v162
	v_sub_f32_e32 v165, v165, v201
	v_mul_f32_e32 v164, 0x3fb8aa3b, v164
	v_exp_f32_e32 v231, v163
	v_add_f32_e32 v162, v227, v162
	v_exp_f32_e32 v234, v158
	v_sub_f32_e32 v158, v159, v201
	v_mul_f32_e32 v165, 0x3fb8aa3b, v165
	v_exp_f32_e32 v232, v164
	v_add_f32_e32 v162, v228, v162
	v_mul_f32_e32 v158, 0x3fb8aa3b, v158
	v_exp_f32_e32 v233, v165
	v_add_f32_e32 v162, v229, v162
	v_exp_f32_e32 v235, v158
	v_sub_f32_e32 v158, v160, v201
	v_sub_f32_e32 v159, v188, v201
	v_add_f32_e32 v162, v230, v162
	v_mul_f32_e32 v158, 0x3fb8aa3b, v158
	v_mul_f32_e32 v159, 0x3fb8aa3b, v159
	v_add_f32_e32 v162, v231, v162
	v_exp_f32_e32 v236, v158
	v_sub_f32_e32 v158, v161, v201
	v_exp_f32_e32 v188, v159
	v_sub_f32_e32 v159, v189, v201
	v_add_f32_e32 v162, v232, v162
	v_mul_f32_e32 v158, 0x3fb8aa3b, v158
	v_mul_f32_e32 v159, 0x3fb8aa3b, v159
	v_add_f32_e32 v162, v233, v162
	v_exp_f32_e32 v237, v158
	v_exp_f32_e32 v189, v159
	v_sub_f32_e32 v159, v190, v201
	v_add_f32_e32 v158, v234, v162
	v_mul_f32_e32 v159, 0x3fb8aa3b, v159
	v_add_f32_e32 v158, v235, v158
	v_exp_f32_e32 v190, v159
	v_sub_f32_e32 v159, v191, v201
	v_add_f32_e32 v158, v236, v158
	v_mul_f32_e32 v159, 0x3fb8aa3b, v159
	v_add_f32_e32 v158, v237, v158
	v_exp_f32_e32 v191, v159
	v_add_f32_e32 v158, v188, v158
	v_add_f32_e32 v158, v189, v158
	v_add_f32_e32 v158, v190, v158
	v_add_f32_e32 v158, v191, v158
	ds_bpermute_b32 v159, v207, v158
	v_sub_f32_e32 v5, v5, v201
	v_mul_f32_e32 v5, 0x3fb8aa3b, v5
	v_exp_f32_e32 v5, v5
	v_cvt_pk_bf16_f32 v160, v182, v183
	s_waitcnt lgkmcnt(0)
; #define LAS __attribute__((address_space(3)))
; __device__ __forceinline__ unsigned pk2(float lo, float hi) { return f2bf(lo) | (f2bf(hi) << 16); }
; #define MFMA16(a, b, c) __builtin_amdgcn_mfma_f32_16x16x32_bf16((a), (b), (c), 0, 0, 0)
; __device__ __forceinline__ void attn_item(Frame& F, int item) {
;     ...
; #pragma unroll
;         for (int dt = 0; dt < 4; ++dt) {
;             f32x4 o = (f32x4){0.f, 0.f, 0.f, 0.f};
;             const LAS bf16* vrow = Vt + (16 * dt + l15) * VT2_STRIDE + 16 * w + 4 * quad;
; #pragma unroll
;             for (int kk = 0; kk < 5; ++kk) {
;                 const v2u lo = *(const LAS v2u*)(vrow + 32 * kk);
;                 v2u hi = (v2u){0u, 0u}; if (kk < 4) hi = *(const LAS v2u*)(vrow + 32 * kk + 16);
;                 o = MFMA16(join8(lo, hi), pf[kk], o);
;             }
;             v2u ow; ow.x = pk2(o[0] * il, o[1] * il); ow.y = pk2(o[2] * il, o[3] * il);
;             *(v2u*)(F.MIXED + row * D + 512 + qh * 64 + 16 * dt + 4 * quad) = ow;
;         }
	v_add_f32_e32 v158, v158, v159
	ds_bpermute_b32 v159, v208, v158
	v_cvt_pk_bf16_f32 v161, v184, v185
	v_cvt_pk_bf16_f32 v162, v178, v179
	v_cvt_pk_bf16_f32 v163, v180, v181
	v_cvt_pk_bf16_f32 v164, v174, v175
	s_waitcnt lgkmcnt(0)
	v_add_f32_e32 v158, v158, v159
	v_add_f32_e32 v5, v5, v158
	v_cvt_pk_bf16_f32 v158, v186, v1
	v_cvt_pk_bf16_f32 v159, v2, v3
	v_cvt_pk_bf16_f32 v165, v176, v177
	v_cvt_pk_bf16_f32 v170, v170, v171
	v_mfma_f32_16x16x32_bf16 v[166:169], v[78:81], v[158:161], 0
	v_cvt_pk_bf16_f32 v171, v172, v173
	v_cvt_pk_bf16_f32 v172, v226, v227
	v_cvt_pk_bf16_f32 v173, v228, v229
	v_mfma_f32_16x16x32_bf16 v[166:169], v[82:85], v[162:165], v[166:169]
	v_cvt_pk_bf16_f32 v174, v230, v231
	v_cvt_pk_bf16_f32 v175, v232, v233
	v_cvt_pk_bf16_f32 v176, v234, v235
	v_mfma_f32_16x16x32_bf16 v[166:169], v[86:89], v[170:173], v[166:169]
	v_cvt_pk_bf16_f32 v177, v236, v237
	v_rcp_f32_e32 v178, v5
	v_cvt_pk_bf16_f32 v2, v188, v189
	v_mfma_f32_16x16x32_bf16 v[166:169], v[90:93], v[174:177], v[166:169]
	v_cvt_pk_bf16_f32 v3, v190, v191
	v_mov_b32_e32 v5, v4
	s_nop 1
	v_mfma_f32_16x16x32_bf16 v[166:169], v[94:97], v[2:5], v[166:169]
	s_nop 7
	v_mov_b32_e32 v181, v168
	v_mov_b32_e32 v168, v167
	v_mov_b32_e32 v180, v166
	v_pk_mul_f32 v[182:183], v[168:169], v[178:179] op_sel_hi:[1,0]
	v_mfma_f32_16x16x32_bf16 v[166:169], v[98:101], v[158:161], 0
	v_mul_f32_e64 v180, v180, v178
	v_mul_f32_e64 v181, v181, v178
	v_and_b32_sdwa v1, v181, v225 dst_sel:DWORD dst_unused:UNUSED_PAD src0_sel:WORD_1 src1_sel:DWORD
	v_mfma_f32_16x16x32_bf16 v[166:169], v[102:105], v[162:165], v[166:169]
	v_and_b32_sdwa v179, v180, v225 dst_sel:DWORD dst_unused:UNUSED_PAD src0_sel:WORD_1 src1_sel:DWORD
	v_add3_u32 v179, v180, v179, s66
	v_add3_u32 v1, v181, v1, s66
	v_mfma_f32_16x16x32_bf16 v[166:169], v[106:109], v[170:173], v[166:169]
	v_and_b32_sdwa v180, v183, v225 dst_sel:DWORD dst_unused:UNUSED_PAD src0_sel:WORD_1 src1_sel:DWORD
	v_and_b32_sdwa v181, v182, v225 dst_sel:DWORD dst_unused:UNUSED_PAD src0_sel:WORD_1 src1_sel:DWORD
	v_add3_u32 v180, v183, v180, s66
	v_mfma_f32_16x16x32_bf16 v[166:169], v[110:113], v[174:177], v[166:169]
	v_add3_u32 v181, v182, v181, s66
	v_and_b32_e32 v180, 0xffff0000, v180
	v_and_b32_e32 v182, 0xffff0000, v181
	v_mfma_f32_16x16x32_bf16 v[166:169], v[114:117], v[2:5], v[166:169]
	v_or_b32_sdwa v181, v180, v1 dst_sel:DWORD dst_unused:UNUSED_PAD src0_sel:DWORD src1_sel:WORD_1
	v_or_b32_sdwa v180, v182, v179 dst_sel:DWORD dst_unused:UNUSED_PAD src0_sel:DWORD src1_sel:WORD_1
	v_lshl_add_u64 v[182:183], v[204:205], 0, s[82:83]
	global_store_dwordx2 v[182:183], v[180:181], off offset:-64
	s_add_u32 s82, s82, 0x80
	s_nop 2
	v_mov_b32_e32 v181, v168
	v_mov_b32_e32 v168, v167
	v_mov_b32_e32 v180, v166
	v_pk_mul_f32 v[184:185], v[168:169], v[178:179] op_sel_hi:[1,0]
	v_mfma_f32_16x16x32_bf16 v[166:169], v[118:121], v[158:161], 0
	v_mul_f32_e64 v180, v180, v178
	v_mul_f32_e64 v181, v181, v178
	s_addc_u32 s83, s83, 0
	v_and_b32_sdwa v1, v181, v225 dst_sel:DWORD dst_unused:UNUSED_PAD src0_sel:WORD_1 src1_sel:DWORD
	v_mfma_f32_16x16x32_bf16 v[158:161], v[138:141], v[158:161], 0
	v_and_b32_sdwa v179, v180, v225 dst_sel:DWORD dst_unused:UNUSED_PAD src0_sel:WORD_1 src1_sel:DWORD
	v_add3_u32 v179, v180, v179, s66
	v_add3_u32 v1, v181, v1, s66
	v_mfma_f32_16x16x32_bf16 v[166:169], v[122:125], v[162:165], v[166:169]
	v_and_b32_sdwa v180, v185, v225 dst_sel:DWORD dst_unused:UNUSED_PAD src0_sel:WORD_1 src1_sel:DWORD
	v_and_b32_sdwa v181, v184, v225 dst_sel:DWORD dst_unused:UNUSED_PAD src0_sel:WORD_1 src1_sel:DWORD
	v_add3_u32 v180, v185, v180, s66
	v_mfma_f32_16x16x32_bf16 v[158:161], v[142:145], v[162:165], v[158:161]
	v_add3_u32 v181, v184, v181, s66
	v_and_b32_e32 v180, 0xffff0000, v180
	v_and_b32_e32 v184, 0xffff0000, v181
	v_mfma_f32_16x16x32_bf16 v[166:169], v[126:129], v[170:173], v[166:169]
	v_or_b32_sdwa v181, v180, v1 dst_sel:DWORD dst_unused:UNUSED_PAD src0_sel:DWORD src1_sel:WORD_1
	v_or_b32_sdwa v180, v184, v179 dst_sel:DWORD dst_unused:UNUSED_PAD src0_sel:DWORD src1_sel:WORD_1
	global_store_dwordx2 v[182:183], v[180:181], off offset:-32
	v_mfma_f32_16x16x32_bf16 v[158:161], v[146:149], v[170:173], v[158:161]
	s_add_u32 s78, s78, 4
	s_addc_u32 s79, s79, 0
	s_cmpk_lg_i32 s82, 0x200
	v_mfma_f32_16x16x32_bf16 v[166:169], v[130:133], v[174:177], v[166:169]
	v_mfma_f32_16x16x32_bf16 v[158:161], v[150:153], v[174:177], v[158:161]
	v_mfma_f32_16x16x32_bf16 v[166:169], v[134:137], v[2:5], v[166:169]
	v_mfma_f32_16x16x32_bf16 v[158:161], v[154:157], v[2:5], v[158:161]
	s_nop 6
	v_mov_b32_e32 v181, v168
	v_mov_b32_e32 v168, v167
	v_mov_b32_e32 v180, v166
	v_pk_mul_f32 v[166:167], v[168:169], v[178:179] op_sel_hi:[1,0]
	v_pk_mul_f32 v[180:181], v[180:181], v[178:179] op_sel_hi:[1,0]
	v_and_b32_sdwa v163, v166, v225 dst_sel:DWORD dst_unused:UNUSED_PAD src0_sel:WORD_1 src1_sel:DWORD
	v_mov_b32_e32 v2, v158
	v_mov_b32_e32 v3, v160
	v_add3_u32 v163, v166, v163, s66
	v_pk_mul_f32 v[2:3], v[2:3], v[178:179] op_sel_hi:[1,0]
	v_mov_b32_e32 v160, v159
	v_and_b32_e32 v164, 0xffff0000, v163
	v_cvt_pk_bf16_f32 v163, v181, v167
	v_pk_mul_f32 v[158:159], v[160:161], v[178:179] op_sel_hi:[1,0]
	v_and_b32_sdwa v168, v180, v225 dst_sel:DWORD dst_unused:UNUSED_PAD src0_sel:WORD_1 src1_sel:DWORD
	v_add3_u32 v168, v180, v168, s66
	v_or_b32_sdwa v162, v164, v168 dst_sel:DWORD dst_unused:UNUSED_PAD src0_sel:DWORD src1_sel:WORD_1
	v_cvt_pk_bf16_f32 v3, v3, v159
	v_cvt_pk_bf16_f32 v2, v2, v158
	global_store_dwordx2 v[182:183], v[162:163], off
	global_store_dwordx2 v[182:183], v[2:3], off offset:32
	s_cbranch_scc0 .LBB0_485

; __device__ __forceinline__ unsigned pk2(float lo, float hi) { return f2bf(lo) | (f2bf(hi) << 16); }
; __device__ __forceinline__ void hgrn_correct(Frame& F, int item) {
;     ...
; #pragma unroll
;     for (int tt = 0; tt < 2; ++tt) {
;         const size_t row = row0 + 32 * w + 16 * tt + l15;
;         float ss = 0.f;
; #pragma unroll
;         for (int vt = 0; vt < 8; ++vt) { const f32x4 o = O[vt][tt] + OL[tt][vt]; O[vt][tt] = o; ss += (o[0] * o[0] + o[1] * o[1]) + (o[2] * o[2] + o[3] * o[3]); }
;         ss += __shfl_xor(ss, 16); ss += __shfl_xor(ss, 32);
;         const float rs = __builtin_amdgcn_rsqf(ss * (1.0f / 128.0f) + EPS);
;         bf16* mp = F.MIXED + row * D + h * 128 + 4 * quad;
; #pragma unroll
;         for (int vt = 0; vt < 8; ++vt) {
;             const v2u gw = GW[tt][vt];
;             const f32x4 og = *(const f32x4*)(F.ogain + 16 * vt + 4 * quad);
;             const f32x4 o = O[vt][tt];
;             v2u ow; ow.x = pk2(o[0] * rs * og[0] * bflo(gw.x), o[1] * rs * og[1] * bfhi(gw.x)); ow.y = pk2(o[2] * rs * og[2] * bflo(gw.y), o[3] * rs * og[3] * bfhi(gw.y));
;             *(v2u*)(mp + 16 * vt) = ow;
.LBB0_551:
	s_waitcnt vmcnt(30)
	v_pk_add_f32 v[82:83], v[120:121], v[152:153]
	v_pk_add_f32 v[84:85], v[118:119], v[150:151]
	ds_read_b128 v[118:121], v224 offset:36864
	s_nop 0
	v_and_b32_e32 v71, 64, v209
	v_xor_b32_e32 v70, 16, v209
	v_add_u32_e32 v72, 64, v71
	v_cmp_lt_i32_e32 vcc, v70, v72
	v_pk_add_f32 v[122:123], v[122:123], v[146:147]
	v_pk_add_f32 v[92:93], v[124:125], v[148:149]
	v_cndmask_b32_e32 v70, v209, v70, vcc
	v_mov_b32_e32 v74, v85
	v_mov_b32_e32 v75, v123
	v_lshlrev_b32_e32 v73, 2, v70
	v_mov_b32_e32 v70, v84
	v_mov_b32_e32 v71, v122
	v_pk_mul_f32 v[74:75], v[74:75], v[74:75]
	v_mov_b32_e32 v76, v83
	v_mov_b32_e32 v77, v93
	v_pk_fma_f32 v[70:71], v[70:71], v[70:71], v[74:75]
	v_mov_b32_e32 v74, v82
	v_mov_b32_e32 v75, v92
	v_pk_mul_f32 v[76:77], v[76:77], v[76:77]
	s_waitcnt vmcnt(30)
	v_pk_add_f32 v[116:117], v[116:117], v[128:129]
	v_pk_fma_f32 v[74:75], v[74:75], v[74:75], v[76:77]
	v_pk_add_f32 v[114:115], v[114:115], v[126:127]
	v_pk_add_f32 v[70:71], v[70:71], v[74:75]
	v_pk_mul_f32 v[74:75], v[116:117], v[116:117]
	v_pk_add_f32 v[70:71], v[70:71], v[70:71] op_sel_hi:[0,1]
	v_pk_mul_f32 v[76:77], v[114:115], v[114:115]
	s_waitcnt vmcnt(29)
	v_pk_add_f32 v[110:111], v[110:111], v[130:131]
	v_pk_mov_b32 v[78:79], v[76:77], v[74:75] op_sel:[1,0]
	v_mov_b32_e32 v77, v75
	v_pk_add_f32 v[112:113], v[112:113], v[132:133]
	v_mul_f32_e32 v70, v110, v110
	v_pk_add_f32 v[74:75], v[78:79], v[76:77]
	v_pk_fma_f32 v[76:77], v[110:111], v[110:111], v[70:71] op_sel_hi:[1,1,0]
	v_mul_f32_e32 v70, v112, v112
	v_pk_add_f32 v[74:75], v[74:75], v[74:75] op_sel_hi:[0,1]
	v_pk_fma_f32 v[78:79], v[112:113], v[112:113], v[70:71] op_sel_hi:[1,1,0]
	s_waitcnt vmcnt(24)
	v_pk_add_f32 v[86:87], v[108:109], v[144:145]
	v_pk_add_f32 v[88:89], v[106:107], v[142:143]
	v_mul_f32_e32 v74, v86, v86
	v_mul_f32_e32 v76, v88, v88
	v_mul_f32_e32 v78, v89, v89
	v_mul_f32_e32 v70, v87, v87
	v_pk_add_f32 v[76:77], v[76:77], v[78:79]
	v_pk_add_f32 v[70:71], v[74:75], v[70:71]
	s_waitcnt vmcnt(23)
	v_pk_add_f32 v[78:79], v[104:105], v[136:137]
	v_pk_add_f32 v[70:71], v[76:77], v[70:71]
	v_pk_add_f32 v[80:81], v[102:103], v[134:135]
	v_pk_add_f32 v[90:91], v[70:71], v[70:71] op_sel_hi:[0,1]
	v_pk_mul_f32 v[70:71], v[78:79], v[78:79]
	v_pk_mul_f32 v[74:75], v[80:81], v[80:81]
	s_waitcnt vmcnt(21)
	v_pk_add_f32 v[68:69], v[96:97], v[68:69]
	v_pk_mov_b32 v[76:77], v[74:75], v[70:71] op_sel:[1,0]
	v_mov_b32_e32 v75, v71
	v_pk_add_f32 v[70:71], v[76:77], v[74:75]
	v_pk_add_f32 v[76:77], v[98:99], v[138:139]
	v_pk_add_f32 v[102:103], v[70:71], v[70:71] op_sel_hi:[0,1]
	v_pk_add_f32 v[74:75], v[100:101], v[140:141]
	v_mul_f32_e32 v70, v76, v76
	v_pk_fma_f32 v[98:99], v[76:77], v[76:77], v[70:71] op_sel_hi:[1,1,0]
	v_mul_f32_e32 v70, v74, v74
	v_pk_fma_f32 v[100:101], v[74:75], v[74:75], v[70:71] op_sel_hi:[1,1,0]
	v_pk_add_f32 v[70:71], v[94:95], v[66:67]
	v_mul_f32_e32 v102, v68, v68
	v_mul_f32_e32 v98, v70, v70
	v_mul_f32_e32 v100, v71, v71
	v_mul_f32_e32 v90, v69, v69
	v_pk_add_f32 v[66:67], v[98:99], v[100:101]
	v_pk_add_f32 v[90:91], v[102:103], v[90:91]
	v_mov_b32_e32 v94, v122
	v_pk_add_f32 v[66:67], v[66:67], v[90:91]
	v_xor_b32_e32 v90, 32, v209
	v_add_f32_e32 v66, v66, v67
	ds_bpermute_b32 v67, v73, v66
	v_cmp_lt_i32_e32 vcc, v90, v72
	v_mov_b32_e32 v95, v92
	v_mov_b32_e32 v92, v123
	v_cndmask_b32_e32 v72, v209, v90, vcc
	v_lshlrev_b32_e32 v90, 2, v72
	s_waitcnt lgkmcnt(0)
	v_add_f32_e32 v66, v66, v67
	ds_bpermute_b32 v67, v90, v66
	s_waitcnt vmcnt(0) lgkmcnt(0)
	v_mov_b32_e32 v96, v118
	v_mov_b32_e32 v97, v120
	v_mov_b32_e32 v120, v119
	v_mov_b32_e32 v100, v84
	s_waitcnt lgkmcnt(0)
	v_add_f32_e32 v66, v66, v67
	v_fmamk_f32 v66, v66, 0x3c000000, v210
	v_rsq_f32_e32 v72, v66
	v_lshl_add_u64 v[66:67], s[0:1], 0, v[204:205]
	v_lshl_add_u64 v[66:67], v[66:67], 0, v[182:183]
	v_lshl_add_u64 v[66:67], v[66:67], 0, v[154:155]
	v_pk_mul_f32 v[94:95], v[94:95], v[72:73] op_sel_hi:[1,0]
	v_pk_mul_f32 v[92:93], v[92:93], v[72:73] op_sel_hi:[1,0]
	v_pk_mul_f32 v[94:95], v[96:97], v[94:95]
	v_lshlrev_b32_e32 v97, 16, v203
	v_lshlrev_b32_e32 v96, 16, v202
	v_pk_mul_f32 v[94:95], v[94:95], v[96:97]
	v_pk_mul_f32 v[92:93], v[120:121], v[92:93]
	v_and_b32_e32 v97, 0xffff0000, v203
	v_and_b32_e32 v96, 0xffff0000, v202
	v_pk_mul_f32 v[92:93], v[92:93], v[96:97]
	v_cvt_pk_bf16_f32 v93, v95, v93
	v_cvt_pk_bf16_f32 v92, v94, v92
	global_store_dwordx2 v[66:67], v[92:93], off
	ds_read_b128 v[92:95], v224 offset:36928
	v_mov_b32_e32 v101, v82
	v_mov_b32_e32 v82, v85
	v_pk_mul_f32 v[84:85], v[100:101], v[72:73] op_sel_hi:[1,0]
	v_pk_mul_f32 v[82:83], v[82:83], v[72:73] op_sel_hi:[1,0]
	v_and_b32_e32 v99, 0xffff0000, v201
	v_and_b32_e32 v98, 0xffff0000, v200
	v_lshlrev_b32_e32 v97, 16, v201
	v_lshlrev_b32_e32 v96, 16, v200
	v_pk_add_f32 v[58:59], v[42:43], v[58:59]
	v_pk_add_f32 v[42:43], v[36:37], v[64:65]
	v_pk_add_f32 v[36:37], v[22:23], v[54:55]
	v_mov_b32_e32 v23, v68
	v_mov_b32_e32 v68, v71
	v_pk_add_f32 v[60:61], v[44:45], v[60:61]
	v_pk_add_f32 v[44:45], v[34:35], v[62:63]
	v_pk_add_f32 v[34:35], v[24:25], v[56:57]
	v_mov_b32_e32 v22, v70
	v_pk_mul_f32 v[24:25], v[68:69], v[72:73] op_sel_hi:[1,0]
	v_pk_mul_f32 v[22:23], v[22:23], v[72:73] op_sel_hi:[1,0]
	s_add_i32 s16, s16, s3
	s_add_i32 s20, s20, s3
	s_cmpk_lt_i32 s16, 0x100
	s_waitcnt lgkmcnt(0)
; __device__ __forceinline__ unsigned pk2(float lo, float hi) { return f2bf(lo) | (f2bf(hi) << 16); }
; __device__ __forceinline__ void hgrn_correct(Frame& F, int item) {
;     ...
;         bf16* mp = F.MIXED + row * D + h * 128 + 4 * quad;
; #pragma unroll
;         for (int vt = 0; vt < 8; ++vt) {
;             const v2u gw = GW[tt][vt];
;             const f32x4 og = *(const f32x4*)(F.ogain + 16 * vt + 4 * quad);
;             const f32x4 o = O[vt][tt];
;             v2u ow; ow.x = pk2(o[0] * rs * og[0] * bflo(gw.x), o[1] * rs * og[1] * bfhi(gw.x)); ow.y = pk2(o[2] * rs * og[2] * bflo(gw.y), o[3] * rs * og[3] * bfhi(gw.y));
;             *(v2u*)(mp + 16 * vt) = ow;
;         }
	v_mov_b32_e32 v101, v94
	v_mov_b32_e32 v94, v93
	v_mov_b32_e32 v100, v92
	v_pk_mul_f32 v[82:83], v[94:95], v[82:83]
	v_pk_mul_f32 v[84:85], v[100:101], v[84:85]
	v_pk_mul_f32 v[82:83], v[82:83], v[98:99]
	v_pk_mul_f32 v[84:85], v[84:85], v[96:97]
	v_cvt_pk_bf16_f32 v83, v85, v83
	v_cvt_pk_bf16_f32 v82, v84, v82
	global_store_dwordx2 v[66:67], v[82:83], off offset:32
	ds_read_b128 v[82:85], v224 offset:36992
	v_mov_b32_e32 v97, v116
	v_mov_b32_e32 v116, v115
	v_mov_b32_e32 v96, v114
	v_pk_mul_f32 v[98:99], v[116:117], v[72:73] op_sel_hi:[1,0]
	v_and_b32_e32 v95, 0xffff0000, v199
	v_and_b32_e32 v94, 0xffff0000, v198
	v_pk_mul_f32 v[96:97], v[96:97], v[72:73] op_sel_hi:[1,0]
	v_lshlrev_b32_e32 v93, 16, v199
	v_lshlrev_b32_e32 v92, 16, v198
	s_waitcnt lgkmcnt(0)
	v_mov_b32_e32 v101, v84
	v_mov_b32_e32 v84, v83
	v_mov_b32_e32 v100, v82
	v_pk_mul_f32 v[84:85], v[84:85], v[98:99]
	v_pk_mul_f32 v[82:83], v[100:101], v[96:97]
	v_pk_mul_f32 v[84:85], v[84:85], v[94:95]
	v_pk_mul_f32 v[82:83], v[82:83], v[92:93]
	v_cvt_pk_bf16_f32 v83, v83, v85
	v_cvt_pk_bf16_f32 v82, v82, v84
	global_store_dwordx2 v[66:67], v[82:83], off offset:64
	ds_read_b128 v[82:85], v224 offset:37056
	v_mov_b32_e32 v97, v112
	v_mov_b32_e32 v112, v111
	v_mov_b32_e32 v96, v110
	v_pk_mul_f32 v[98:99], v[112:113], v[72:73] op_sel_hi:[1,0]
	v_and_b32_e32 v95, 0xffff0000, v197
	v_and_b32_e32 v94, 0xffff0000, v196
	v_pk_mul_f32 v[96:97], v[96:97], v[72:73] op_sel_hi:[1,0]
	v_lshlrev_b32_e32 v93, 16, v197
	v_lshlrev_b32_e32 v92, 16, v196
	s_waitcnt lgkmcnt(0)
	v_mov_b32_e32 v101, v84
	v_mov_b32_e32 v84, v83
	v_mov_b32_e32 v100, v82
	v_pk_mul_f32 v[84:85], v[84:85], v[98:99]
	v_pk_mul_f32 v[82:83], v[100:101], v[96:97]
	v_pk_mul_f32 v[84:85], v[84:85], v[94:95]
	v_pk_mul_f32 v[82:83], v[82:83], v[92:93]
	v_cvt_pk_bf16_f32 v83, v83, v85
	v_cvt_pk_bf16_f32 v82, v82, v84
	global_store_dwordx2 v[66:67], v[82:83], off offset:96
	ds_read_b128 v[82:85], v224 offset:37120
	v_mov_b32_e32 v96, v88
	v_mov_b32_e32 v97, v86
	v_mov_b32_e32 v86, v89
	v_pk_mul_f32 v[88:89], v[96:97], v[72:73] op_sel_hi:[1,0]
	v_pk_mul_f32 v[86:87], v[86:87], v[72:73] op_sel_hi:[1,0]
	v_and_b32_e32 v95, 0xffff0000, v195
	v_and_b32_e32 v94, 0xffff0000, v194
	v_lshlrev_b32_e32 v93, 16, v195
	v_lshlrev_b32_e32 v92, 16, v194
	s_waitcnt lgkmcnt(0)
	v_mov_b32_e32 v97, v84
	v_mov_b32_e32 v84, v83
	v_mov_b32_e32 v96, v82
	v_pk_mul_f32 v[84:85], v[84:85], v[86:87]
	v_pk_mul_f32 v[82:83], v[96:97], v[88:89]
	v_pk_mul_f32 v[84:85], v[84:85], v[94:95]
	v_pk_mul_f32 v[82:83], v[82:83], v[92:93]
	v_cvt_pk_bf16_f32 v83, v83, v85
	v_cvt_pk_bf16_f32 v82, v82, v84
	global_store_dwordx2 v[66:67], v[82:83], off offset:128
	ds_read_b128 v[82:85], v224 offset:37184
	v_mov_b32_e32 v92, v80
	v_mov_b32_e32 v93, v78
	v_mov_b32_e32 v78, v81
	v_pk_mul_f32 v[80:81], v[92:93], v[72:73] op_sel_hi:[1,0]
	v_pk_mul_f32 v[78:79], v[78:79], v[72:73] op_sel_hi:[1,0]
	v_and_b32_e32 v89, 0xffff0000, v193
	v_and_b32_e32 v88, 0xffff0000, v192
	v_lshlrev_b32_e32 v87, 16, v193
	v_lshlrev_b32_e32 v86, 16, v192
	s_waitcnt lgkmcnt(0)
	v_mov_b32_e32 v93, v84
	v_mov_b32_e32 v84, v83
	v_mov_b32_e32 v92, v82
	v_pk_mul_f32 v[78:79], v[84:85], v[78:79]
	v_pk_mul_f32 v[80:81], v[92:93], v[80:81]
	v_pk_mul_f32 v[78:79], v[78:79], v[88:89]
	v_pk_mul_f32 v[80:81], v[80:81], v[86:87]
	v_cvt_pk_bf16_f32 v79, v81, v79
	v_cvt_pk_bf16_f32 v78, v80, v78
	global_store_dwordx2 v[66:67], v[78:79], off offset:160
	ds_read_b128 v[78:81], v224 offset:37248
	v_mov_b32_e32 v86, v76
	v_mov_b32_e32 v87, v74
	v_mov_b32_e32 v74, v77
	v_pk_mul_f32 v[76:77], v[86:87], v[72:73] op_sel_hi:[1,0]
	v_pk_mul_f32 v[74:75], v[74:75], v[72:73] op_sel_hi:[1,0]
	v_and_b32_e32 v85, 0xffff0000, v191
	v_and_b32_e32 v84, 0xffff0000, v190
	v_lshlrev_b32_e32 v83, 16, v191
	v_lshlrev_b32_e32 v82, 16, v190
	s_waitcnt lgkmcnt(0)
	v_mov_b32_e32 v87, v80
	v_mov_b32_e32 v80, v79
	v_mov_b32_e32 v86, v78
	v_pk_mul_f32 v[74:75], v[74:75], v[80:81]
	v_pk_mul_f32 v[76:77], v[76:77], v[86:87]
	v_pk_mul_f32 v[74:75], v[74:75], v[84:85]
	v_pk_mul_f32 v[76:77], v[76:77], v[82:83]
	v_cvt_pk_bf16_f32 v75, v77, v75
	v_cvt_pk_bf16_f32 v74, v76, v74
	global_store_dwordx2 v[66:67], v[74:75], off offset:192
	ds_read_b128 v[74:77], v224 offset:37312
	v_and_b32_e32 v81, 0xffff0000, v189
	v_and_b32_e32 v80, 0xffff0000, v188
	v_lshlrev_b32_e32 v79, 16, v189
	v_lshlrev_b32_e32 v78, 16, v188
	s_waitcnt lgkmcnt(0)
; __device__ __forceinline__ unsigned pk2(float lo, float hi) { return f2bf(lo) | (f2bf(hi) << 16); }
; __device__ __forceinline__ void hgrn_correct(Frame& F, int item) {
;     ...
;     for (int tt = 0; tt < 2; ++tt) {
;         const size_t row = row0 + 32 * w + 16 * tt + l15;
;         float ss = 0.f;
; #pragma unroll
;         for (int vt = 0; vt < 8; ++vt) { const f32x4 o = O[vt][tt] + OL[tt][vt]; O[vt][tt] = o; ss += (o[0] * o[0] + o[1] * o[1]) + (o[2] * o[2] + o[3] * o[3]); }
;         ss += __shfl_xor(ss, 16); ss += __shfl_xor(ss, 32);
;         const float rs = __builtin_amdgcn_rsqf(ss * (1.0f / 128.0f) + EPS);
;         bf16* mp = F.MIXED + row * D + h * 128 + 4 * quad;
; #pragma unroll
;         for (int vt = 0; vt < 8; ++vt) {
;             const v2u gw = GW[tt][vt];
;             const f32x4 og = *(const f32x4*)(F.ogain + 16 * vt + 4 * quad);
;             const f32x4 o = O[vt][tt];
;             v2u ow; ow.x = pk2(o[0] * rs * og[0] * bflo(gw.x), o[1] * rs * og[1] * bfhi(gw.x)); ow.y = pk2(o[2] * rs * og[2] * bflo(gw.y), o[3] * rs * og[3] * bfhi(gw.y));
;             *(v2u*)(mp + 16 * vt) = ow;
;         }
	v_mov_b32_e32 v55, v76
	v_mov_b32_e32 v76, v75
	v_mov_b32_e32 v54, v74
	v_pk_mul_f32 v[24:25], v[24:25], v[76:77]
	v_pk_mul_f32 v[22:23], v[22:23], v[54:55]
	v_pk_mul_f32 v[24:25], v[24:25], v[80:81]
	v_pk_mul_f32 v[22:23], v[22:23], v[78:79]
	v_cvt_pk_bf16_f32 v23, v23, v25
	v_cvt_pk_bf16_f32 v22, v22, v24
	global_store_dwordx2 v[66:67], v[22:23], off offset:224
	ds_read_b128 v[62:65], v224 offset:36864
	v_pk_add_f32 v[56:57], v[2:3], v[26:27]
	v_pk_add_f32 v[26:27], v[8:9], v[32:33]
	v_pk_add_f32 v[22:23], v[12:13], v[40:41]
	v_pk_add_f32 v[8:9], v[16:17], v[48:49]
	v_mov_b32_e32 v12, v45
	v_mov_b32_e32 v13, v59
	v_mov_b32_e32 v16, v43
	v_mov_b32_e32 v17, v61
	v_pk_add_f32 v[54:55], v[4:5], v[28:29]
	v_pk_add_f32 v[28:29], v[6:7], v[30:31]
	v_pk_add_f32 v[24:25], v[10:11], v[38:39]
	v_pk_add_f32 v[10:11], v[14:15], v[46:47]
	v_pk_add_f32 v[2:3], v[20:21], v[52:53]
	v_pk_add_f32 v[4:5], v[18:19], v[50:51]
	v_mov_b32_e32 v6, v44
	v_mov_b32_e32 v7, v58
	v_mov_b32_e32 v14, v42
	v_mov_b32_e32 v15, v60
	v_pk_mul_f32 v[18:19], v[34:35], v[34:35]
	v_pk_mul_f32 v[20:21], v[36:37], v[36:37]
	v_pk_mul_f32 v[12:13], v[12:13], v[12:13]
	v_pk_mul_f32 v[16:17], v[16:17], v[16:17]
	v_pk_mov_b32 v[50:51], v[20:21], v[18:19] op_sel:[1,0]
	v_mov_b32_e32 v21, v19
	v_pk_fma_f32 v[6:7], v[6:7], v[6:7], v[12:13]
	v_pk_fma_f32 v[12:13], v[14:15], v[14:15], v[16:17]
	v_mul_f32_e32 v30, v56, v56
	v_mul_f32_e32 v32, v54, v54
	v_pk_add_f32 v[14:15], v[50:51], v[20:21]
	v_pk_add_f32 v[6:7], v[6:7], v[12:13]
	v_pk_fma_f32 v[18:19], v[56:57], v[56:57], v[30:31] op_sel_hi:[1,1,0]
	v_pk_fma_f32 v[30:31], v[54:55], v[54:55], v[32:33] op_sel_hi:[1,1,0]
	v_pk_add_f32 v[12:13], v[14:15], v[14:15] op_sel_hi:[0,1]
	v_pk_add_f32 v[6:7], v[6:7], v[6:7] op_sel_hi:[0,1]
	v_pk_mul_f32 v[38:39], v[22:23], v[22:23]
	v_pk_mul_f32 v[40:41], v[24:25], v[24:25]
	v_mul_f32_e32 v18, v28, v28
	v_mul_f32_e32 v30, v29, v29
	v_mul_f32_e32 v12, v26, v26
	v_mul_f32_e32 v6, v27, v27
	v_pk_mov_b32 v[32:33], v[40:41], v[38:39] op_sel:[1,0]
	v_mov_b32_e32 v41, v39
	v_pk_add_f32 v[14:15], v[18:19], v[30:31]
	v_pk_add_f32 v[6:7], v[12:13], v[6:7]
	v_mul_f32_e32 v46, v10, v10
	v_mul_f32_e32 v48, v8, v8
	v_pk_add_f32 v[16:17], v[32:33], v[40:41]
	v_pk_add_f32 v[6:7], v[14:15], v[6:7]
	v_pk_fma_f32 v[38:39], v[10:11], v[10:11], v[46:47] op_sel_hi:[1,1,0]
	v_pk_fma_f32 v[46:47], v[8:9], v[8:9], v[48:49] op_sel_hi:[1,1,0]
	v_pk_add_f32 v[16:17], v[16:17], v[16:17] op_sel_hi:[0,1]
	v_pk_add_f32 v[6:7], v[6:7], v[6:7] op_sel_hi:[0,1]
	v_mul_f32_e32 v38, v4, v4
	v_mul_f32_e32 v46, v5, v5
	v_mul_f32_e32 v16, v2, v2
	v_mul_f32_e32 v6, v3, v3
	v_pk_add_f32 v[18:19], v[38:39], v[46:47]
	v_pk_add_f32 v[6:7], v[16:17], v[6:7]
	v_lshlrev_b32_e32 v15, 16, v185
	v_pk_add_f32 v[6:7], v[18:19], v[6:7]
	v_mov_b32_e32 v18, v58
	v_add_f32_e32 v12, v6, v7
	ds_bpermute_b32 v13, v73, v12
	v_mov_b32_e32 v19, v60
	v_mov_b32_e32 v60, v59
	v_lshlrev_b32_e32 v14, 16, v184
	v_and_b32_e32 v17, 0xffff0000, v185
	s_waitcnt lgkmcnt(0)
	v_add_f32_e32 v12, v12, v13
	ds_bpermute_b32 v13, v90, v12
	v_and_b32_e32 v16, 0xffff0000, v184
	v_lshl_add_u64 v[6:7], s[0:1], 0, v[186:187]
	v_lshl_add_u64 v[6:7], v[6:7], 0, v[182:183]
	v_lshl_add_u64 v[6:7], v[6:7], 0, v[154:155]
	s_waitcnt lgkmcnt(0)
	v_add_f32_e32 v12, v12, v13
	v_fmamk_f32 v12, v12, 0x3c000000, v210
	v_rsq_f32_e32 v12, v12
	s_waitcnt lgkmcnt(0)
	v_mov_b32_e32 v30, v62
	v_pk_mul_f32 v[18:19], v[18:19], v[12:13] op_sel_hi:[1,0]
	v_pk_mul_f32 v[20:21], v[60:61], v[12:13] op_sel_hi:[1,0]
	v_mov_b32_e32 v31, v64
	v_mov_b32_e32 v64, v63
	v_pk_mul_f32 v[18:19], v[30:31], v[18:19]
	v_pk_mul_f32 v[20:21], v[64:65], v[20:21]
	v_pk_mul_f32 v[14:15], v[18:19], v[14:15]
	v_pk_mul_f32 v[16:17], v[20:21], v[16:17]
	v_and_b32_sdwa v13, v15, v211 dst_sel:DWORD dst_unused:UNUSED_PAD src0_sel:WORD_1 src1_sel:DWORD
	v_and_b32_sdwa v19, v17, v211 dst_sel:DWORD dst_unused:UNUSED_PAD src0_sel:WORD_1 src1_sel:DWORD
	v_add3_u32 v13, v15, v13, s19
	v_add3_u32 v15, v17, v19, s19
	v_and_b32_e32 v15, 0xffff0000, v15
	v_or_b32_sdwa v15, v15, v13 dst_sel:DWORD dst_unused:UNUSED_PAD src0_sel:DWORD src1_sel:WORD_1
	v_cvt_pk_bf16_f32 v14, v14, v16
	global_store_dwordx2 v[6:7], v[14:15], off
	ds_read_b128 v[14:17], v224 offset:36928
	v_mov_b32_e32 v30, v44
	v_mov_b32_e32 v31, v42
	v_mov_b32_e32 v42, v45
	v_pk_mul_f32 v[30:31], v[30:31], v[12:13] op_sel_hi:[1,0]
	v_pk_mul_f32 v[32:33], v[42:43], v[12:13] op_sel_hi:[1,0]
	v_lshlrev_b32_e32 v19, 16, v181
	v_lshlrev_b32_e32 v18, 16, v180
	v_and_b32_e32 v21, 0xffff0000, v181
	v_and_b32_e32 v20, 0xffff0000, v180
	s_waitcnt lgkmcnt(0)
	v_mov_b32_e32 v38, v14
	v_mov_b32_e32 v39, v16
	v_mov_b32_e32 v16, v15
	v_pk_mul_f32 v[14:15], v[38:39], v[30:31]
	v_pk_mul_f32 v[16:17], v[16:17], v[32:33]
	v_pk_mul_f32 v[14:15], v[14:15], v[18:19]
	v_pk_mul_f32 v[16:17], v[16:17], v[20:21]
	v_and_b32_sdwa v13, v15, v211 dst_sel:DWORD dst_unused:UNUSED_PAD src0_sel:WORD_1 src1_sel:DWORD
	v_and_b32_sdwa v19, v17, v211 dst_sel:DWORD dst_unused:UNUSED_PAD src0_sel:WORD_1 src1_sel:DWORD
	v_add3_u32 v13, v15, v13, s19
	v_add3_u32 v15, v17, v19, s19
	v_and_b32_e32 v15, 0xffff0000, v15
	v_or_b32_sdwa v15, v15, v13 dst_sel:DWORD dst_unused:UNUSED_PAD src0_sel:DWORD src1_sel:WORD_1
	v_cvt_pk_bf16_f32 v14, v14, v16
	global_store_dwordx2 v[6:7], v[14:15], off offset:32
	ds_read_b128 v[14:17], v224 offset:36992
	v_mov_b32_e32 v30, v36
	v_mov_b32_e32 v31, v34
	v_mov_b32_e32 v34, v37
	v_pk_mul_f32 v[30:31], v[30:31], v[12:13] op_sel_hi:[1,0]
	v_pk_mul_f32 v[32:33], v[34:35], v[12:13] op_sel_hi:[1,0]
	v_lshlrev_b32_e32 v19, 16, v179
	v_lshlrev_b32_e32 v18, 16, v178
	v_and_b32_e32 v21, 0xffff0000, v179
	v_and_b32_e32 v20, 0xffff0000, v178
	s_waitcnt lgkmcnt(0)
; __device__ __forceinline__ unsigned pk2(float lo, float hi) { return f2bf(lo) | (f2bf(hi) << 16); }
; __device__ __forceinline__ void hgrn_correct(Frame& F, int item) {
;     ...
;         bf16* mp = F.MIXED + row * D + h * 128 + 4 * quad;
; #pragma unroll
;         for (int vt = 0; vt < 8; ++vt) {
;             const v2u gw = GW[tt][vt];
;             const f32x4 og = *(const f32x4*)(F.ogain + 16 * vt + 4 * quad);
;             const f32x4 o = O[vt][tt];
;             v2u ow; ow.x = pk2(o[0] * rs * og[0] * bflo(gw.x), o[1] * rs * og[1] * bfhi(gw.x)); ow.y = pk2(o[2] * rs * og[2] * bflo(gw.y), o[3] * rs * og[3] * bfhi(gw.y));
;             *(v2u*)(mp + 16 * vt) = ow;
;         }
;     }
;     __syncthreads();
	v_mov_b32_e32 v34, v14
	v_mov_b32_e32 v35, v16
	v_mov_b32_e32 v16, v15
	v_pk_mul_f32 v[14:15], v[30:31], v[34:35]
	v_pk_mul_f32 v[16:17], v[32:33], v[16:17]
	v_pk_mul_f32 v[14:15], v[14:15], v[18:19]
	v_pk_mul_f32 v[16:17], v[16:17], v[20:21]
	v_and_b32_sdwa v13, v15, v211 dst_sel:DWORD dst_unused:UNUSED_PAD src0_sel:WORD_1 src1_sel:DWORD
	v_and_b32_sdwa v19, v17, v211 dst_sel:DWORD dst_unused:UNUSED_PAD src0_sel:WORD_1 src1_sel:DWORD
	v_add3_u32 v13, v15, v13, s19
	v_add3_u32 v15, v17, v19, s19
	v_and_b32_e32 v15, 0xffff0000, v15
	v_or_b32_sdwa v15, v15, v13 dst_sel:DWORD dst_unused:UNUSED_PAD src0_sel:DWORD src1_sel:WORD_1
	v_cvt_pk_bf16_f32 v14, v14, v16
	global_store_dwordx2 v[6:7], v[14:15], off offset:64
	ds_read_b128 v[14:17], v224 offset:37056
	v_mov_b32_e32 v30, v56
	v_mov_b32_e32 v31, v54
	v_mov_b32_e32 v54, v57
	v_pk_mul_f32 v[30:31], v[30:31], v[12:13] op_sel_hi:[1,0]
	v_pk_mul_f32 v[32:33], v[54:55], v[12:13] op_sel_hi:[1,0]
	v_lshlrev_b32_e32 v19, 16, v177
	v_lshlrev_b32_e32 v18, 16, v176
	v_and_b32_e32 v21, 0xffff0000, v177
	v_and_b32_e32 v20, 0xffff0000, v176
	s_waitcnt lgkmcnt(0)
	v_mov_b32_e32 v34, v14
	v_mov_b32_e32 v35, v16
	v_mov_b32_e32 v16, v15
	v_pk_mul_f32 v[14:15], v[30:31], v[34:35]
	v_pk_mul_f32 v[16:17], v[32:33], v[16:17]
	v_pk_mul_f32 v[14:15], v[14:15], v[18:19]
	v_pk_mul_f32 v[16:17], v[16:17], v[20:21]
	v_and_b32_sdwa v13, v15, v211 dst_sel:DWORD dst_unused:UNUSED_PAD src0_sel:WORD_1 src1_sel:DWORD
	v_and_b32_sdwa v19, v17, v211 dst_sel:DWORD dst_unused:UNUSED_PAD src0_sel:WORD_1 src1_sel:DWORD
	v_add3_u32 v13, v15, v13, s19
	v_add3_u32 v15, v17, v19, s19
	v_and_b32_e32 v15, 0xffff0000, v15
	v_or_b32_sdwa v15, v15, v13 dst_sel:DWORD dst_unused:UNUSED_PAD src0_sel:DWORD src1_sel:WORD_1
	v_cvt_pk_bf16_f32 v14, v14, v16
	global_store_dwordx2 v[6:7], v[14:15], off offset:96
	ds_read_b128 v[14:17], v224 offset:37120
	v_mov_b32_e32 v30, v28
	v_mov_b32_e32 v31, v26
	v_mov_b32_e32 v26, v29
	v_pk_mul_f32 v[28:29], v[30:31], v[12:13] op_sel_hi:[1,0]
	v_pk_mul_f32 v[26:27], v[26:27], v[12:13] op_sel_hi:[1,0]
	v_lshlrev_b32_e32 v19, 16, v175
	v_lshlrev_b32_e32 v18, 16, v174
	v_and_b32_e32 v21, 0xffff0000, v175
	v_and_b32_e32 v20, 0xffff0000, v174
	s_waitcnt lgkmcnt(0)
	v_mov_b32_e32 v30, v14
	v_mov_b32_e32 v31, v16
	v_mov_b32_e32 v16, v15
	v_pk_mul_f32 v[14:15], v[28:29], v[30:31]
	v_pk_mul_f32 v[16:17], v[26:27], v[16:17]
	v_pk_mul_f32 v[14:15], v[14:15], v[18:19]
	v_pk_mul_f32 v[16:17], v[16:17], v[20:21]
	v_and_b32_sdwa v13, v15, v211 dst_sel:DWORD dst_unused:UNUSED_PAD src0_sel:WORD_1 src1_sel:DWORD
	v_and_b32_sdwa v19, v17, v211 dst_sel:DWORD dst_unused:UNUSED_PAD src0_sel:WORD_1 src1_sel:DWORD
	v_add3_u32 v13, v15, v13, s19
	v_add3_u32 v15, v17, v19, s19
	v_and_b32_e32 v15, 0xffff0000, v15
	v_or_b32_sdwa v15, v15, v13 dst_sel:DWORD dst_unused:UNUSED_PAD src0_sel:DWORD src1_sel:WORD_1
	v_cvt_pk_bf16_f32 v14, v14, v16
	global_store_dwordx2 v[6:7], v[14:15], off offset:128
	ds_read_b128 v[14:17], v224 offset:37184
	v_mov_b32_e32 v26, v24
	v_mov_b32_e32 v27, v22
	v_mov_b32_e32 v22, v25
	v_pk_mul_f32 v[24:25], v[26:27], v[12:13] op_sel_hi:[1,0]
	v_pk_mul_f32 v[22:23], v[22:23], v[12:13] op_sel_hi:[1,0]
	v_lshlrev_b32_e32 v19, 16, v173
	v_lshlrev_b32_e32 v18, 16, v172
	v_and_b32_e32 v21, 0xffff0000, v173
	v_and_b32_e32 v20, 0xffff0000, v172
	s_waitcnt lgkmcnt(0)
	v_mov_b32_e32 v26, v14
	v_mov_b32_e32 v27, v16
	v_mov_b32_e32 v16, v15
	v_pk_mul_f32 v[14:15], v[24:25], v[26:27]
	v_pk_mul_f32 v[16:17], v[22:23], v[16:17]
	v_pk_mul_f32 v[14:15], v[14:15], v[18:19]
	v_pk_mul_f32 v[16:17], v[16:17], v[20:21]
	v_and_b32_sdwa v13, v15, v211 dst_sel:DWORD dst_unused:UNUSED_PAD src0_sel:WORD_1 src1_sel:DWORD
	v_and_b32_sdwa v19, v17, v211 dst_sel:DWORD dst_unused:UNUSED_PAD src0_sel:WORD_1 src1_sel:DWORD
	v_add3_u32 v13, v15, v13, s19
	v_add3_u32 v15, v17, v19, s19
	v_and_b32_e32 v15, 0xffff0000, v15
	v_or_b32_sdwa v15, v15, v13 dst_sel:DWORD dst_unused:UNUSED_PAD src0_sel:DWORD src1_sel:WORD_1
	v_cvt_pk_bf16_f32 v14, v14, v16
	global_store_dwordx2 v[6:7], v[14:15], off offset:160
	ds_read_b128 v[14:17], v224 offset:37248
	v_mov_b32_e32 v22, v10
	v_mov_b32_e32 v23, v8
	v_mov_b32_e32 v8, v11
	v_pk_mul_f32 v[10:11], v[22:23], v[12:13] op_sel_hi:[1,0]
	v_pk_mul_f32 v[8:9], v[8:9], v[12:13] op_sel_hi:[1,0]
	v_and_b32_e32 v21, 0xffff0000, v171
	v_and_b32_e32 v20, 0xffff0000, v170
	v_lshlrev_b32_e32 v19, 16, v171
	v_lshlrev_b32_e32 v18, 16, v170
	s_waitcnt lgkmcnt(0)
	v_mov_b32_e32 v23, v16
	v_mov_b32_e32 v16, v15
	v_mov_b32_e32 v22, v14
	v_pk_mul_f32 v[8:9], v[8:9], v[16:17]
	v_pk_mul_f32 v[10:11], v[10:11], v[22:23]
	v_pk_mul_f32 v[8:9], v[8:9], v[20:21]
	v_pk_mul_f32 v[10:11], v[10:11], v[18:19]
	v_and_b32_sdwa v15, v9, v211 dst_sel:DWORD dst_unused:UNUSED_PAD src0_sel:WORD_1 src1_sel:DWORD
	v_and_b32_sdwa v13, v11, v211 dst_sel:DWORD dst_unused:UNUSED_PAD src0_sel:WORD_1 src1_sel:DWORD
	v_add3_u32 v9, v9, v15, s19
	v_add3_u32 v11, v11, v13, s19
	v_and_b32_e32 v9, 0xffff0000, v9
	v_or_b32_sdwa v9, v9, v11 dst_sel:DWORD dst_unused:UNUSED_PAD src0_sel:DWORD src1_sel:WORD_1
	v_cvt_pk_bf16_f32 v8, v10, v8
	global_store_dwordx2 v[6:7], v[8:9], off offset:192
	ds_read_b128 v[8:11], v224 offset:37312
	v_mov_b32_e32 v18, v4
	v_mov_b32_e32 v19, v2
	v_mov_b32_e32 v2, v5
	v_pk_mul_f32 v[4:5], v[18:19], v[12:13] op_sel_hi:[1,0]
	v_pk_mul_f32 v[2:3], v[2:3], v[12:13] op_sel_hi:[1,0]
	v_and_b32_e32 v17, 0xffff0000, v169
	v_and_b32_e32 v16, 0xffff0000, v168
	v_lshlrev_b32_e32 v15, 16, v169
	v_lshlrev_b32_e32 v14, 16, v168
	s_waitcnt lgkmcnt(0)
	v_mov_b32_e32 v13, v10
	v_mov_b32_e32 v10, v9
	v_mov_b32_e32 v12, v8
	v_pk_mul_f32 v[2:3], v[2:3], v[10:11]
	v_pk_mul_f32 v[4:5], v[4:5], v[12:13]
	v_pk_mul_f32 v[2:3], v[2:3], v[16:17]
	v_pk_mul_f32 v[4:5], v[4:5], v[14:15]
	v_cvt_pk_bf16_f32 v3, v5, v3
	v_cvt_pk_bf16_f32 v2, v4, v2
	global_store_dwordx2 v[6:7], v[2:3], off offset:224
	s_barrier
	s_cbranch_scc0 .LBB0_571

;     __device__ __forceinline__ void operator()(const f32x4 (&acc)[2][2][4][2], const Unit& u, int wr, int wc, int fr, int fq) const {
;     ...
;                 const int row = row0 + ai * HALF + m * 16;
;                 float rs;
;                 if (rsc) rs = rsc[row - rbase];
.LBB0_745:
	v_subrev_u32_e32 v156, s60, v148
	s_andn2_b64 vcc, exec, s[26:27]
	v_lshl_add_u32 v156, v156, 2, s46
	s_cbranch_vccnz .LBB0_747
	ds_read_b32 v228, v156
	ds_read_b32 v229, v156 offset:64
	ds_read_b32 v230, v156 offset:128
	ds_read_b32 v231, v156 offset:192
	ds_read_b32 v232, v156 offset:512
	ds_read_b32 v233, v156 offset:576
	ds_read_b32 v234, v156 offset:640
	ds_read_b32 v235, v156 offset:704
	s_waitcnt lgkmcnt(0)
	v_mov_b32_e32 v150, v228

;     __device__ __forceinline__ void operator()(const f32x4 (&acc)[2][2][4][2], const Unit& u, int wr, int wc, int fr, int fq) const {
;     ...
;                 const int row = row0 + ai * HALF + m * 16;
;                 float rs;
;                 if (rsc) rs = rsc[row - rbase];
.LBB0_749:
	s_andn2_b64 vcc, exec, s[26:27]
	s_cbranch_vccnz .LBB0_751
	v_mov_b32_e32 v116, v229

;     __device__ __forceinline__ void operator()(const f32x4 (&acc)[2][2][4][2], const Unit& u, int wr, int wc, int fr, int fq) const {
;     ...
;                 const int row = row0 + ai * HALF + m * 16;
;                 float rs;
;                 if (rsc) rs = rsc[row - rbase];
.LBB0_753:
	s_andn2_b64 vcc, exec, s[26:27]
	s_cbranch_vccnz .LBB0_755
	v_mov_b32_e32 v100, v230

;     __device__ __forceinline__ void operator()(const f32x4 (&acc)[2][2][4][2], const Unit& u, int wr, int wc, int fr, int fq) const {
;     ...
;                 const int row = row0 + ai * HALF + m * 16;
;                 float rs;
;                 if (rsc) rs = rsc[row - rbase];
.LBB0_757:
	s_andn2_b64 vcc, exec, s[26:27]
	s_cbranch_vccnz .LBB0_759
	v_mov_b32_e32 v84, v231

;     __device__ __forceinline__ void operator()(const f32x4 (&acc)[2][2][4][2], const Unit& u, int wr, int wc, int fr, int fq) const {
;     ...
;                 const int row = row0 + ai * HALF + m * 16;
;                 float rs;
;                 if (rsc) rs = rsc[row - rbase];
.LBB0_761:
	s_andn2_b64 vcc, exec, s[26:27]
	s_cbranch_vccnz .LBB0_763
	v_mov_b32_e32 v68, v232

;     __device__ __forceinline__ void operator()(const f32x4 (&acc)[2][2][4][2], const Unit& u, int wr, int wc, int fr, int fq) const {
;     ...
;                 const int row = row0 + ai * HALF + m * 16;
;                 float rs;
;                 if (rsc) rs = rsc[row - rbase];
.LBB0_765:
	s_andn2_b64 vcc, exec, s[26:27]
	s_cbranch_vccnz .LBB0_767
	v_mov_b32_e32 v52, v233

;     __device__ __forceinline__ void operator()(const f32x4 (&acc)[2][2][4][2], const Unit& u, int wr, int wc, int fr, int fq) const {
;     ...
;                 const int row = row0 + ai * HALF + m * 16;
;                 float rs;
;                 if (rsc) rs = rsc[row - rbase];
.LBB0_769:
	s_andn2_b64 vcc, exec, s[26:27]
	s_cbranch_vccnz .LBB0_771
	v_mov_b32_e32 v36, v234

;     __device__ __forceinline__ void operator()(const f32x4 (&acc)[2][2][4][2], const Unit& u, int wr, int wc, int fr, int fq) const {
;     ...
;                 const int row = row0 + ai * HALF + m * 16;
;                 float rs;
;                 if (rsc) rs = rsc[row - rbase];
.LBB0_773:
	s_andn2_b64 vcc, exec, s[26:27]
	s_cbranch_vccnz .LBB0_775
	v_mov_b32_e32 v20, v235
